# attention item epilogue: gate rows and sub-LN weights loaded in one burst
# speedup vs baseline: 1.0079x; 1.0043x over previous
.LBB0_223:
	s_waitcnt vmcnt(2)
	v_mov_b32_e32 v116, v165
	s_nop 1
	v_permlane16_swap_b32_e32 v165, v116
	v_add_f32_e32 v116, v165, v116
	v_mov_b32_e32 v117, v116
	s_nop 1
	v_permlane32_swap_b32_e32 v116, v117
	v_add_f32_e32 v116, v116, v117
	v_div_scale_f32 v117, s[0:1], v116, v116, 1.0
	v_rcp_f32_e32 v118, v117
	s_waitcnt vmcnt(1)
	v_or_b32_e32 v125, s37, v169
	v_add_u32_e32 v144, s16, v125
	s_lshl_b32 s16, s36, 1
	v_fma_f32 v119, -v117, v118, 1.0
	v_fmac_f32_e32 v118, v119, v118
	v_div_scale_f32 v119, vcc, 1.0, v116, 1.0
	v_mul_f32_e32 v124, v119, v118
	v_fma_f32 v126, -v117, v124, v119
	v_fmac_f32_e32 v124, v126, v118
	v_fma_f32 v117, -v117, v124, v119
	v_mov_b32_e32 v119, v164
	s_nop 1
	v_permlane16_swap_b32_e32 v164, v119
	v_add_f32_e32 v119, v164, v119
	v_mov_b32_e32 v126, v119
	s_nop 1
	v_permlane32_swap_b32_e32 v119, v126
	v_add_f32_e32 v119, v119, v126
	v_div_scale_f32 v126, s[0:1], v119, v119, 1.0
	v_rcp_f32_e32 v127, v126
	v_div_fmas_f32 v117, v117, v118, v124
	v_div_fixup_f32 v124, v117, v116, 1.0
	v_mov_b32_e32 v161, v145
	v_fma_f32 v116, -v126, v127, 1.0
	v_fmac_f32_e32 v127, v116, v127
	v_div_scale_f32 v116, vcc, 1.0, v119, 1.0
	v_mul_f32_e32 v117, v116, v127
	v_fma_f32 v118, -v126, v117, v116
	v_fmac_f32_e32 v117, v118, v127
	v_fma_f32 v116, -v126, v117, v116
	v_div_fmas_f32 v116, v116, v127, v117
	v_div_fixup_f32 v116, v116, v119, 1.0
	v_mul_f32_e32 v126, v172, v116
	v_pk_mul_f32 v[118:119], v[128:129], v[126:127] op_sel_hi:[1,0]
	v_pk_mul_f32 v[116:117], v[130:131], v[126:127] op_sel_hi:[1,0]
	v_pk_fma_f32 v[118:119], v[136:137], v[124:125], v[118:119] op_sel_hi:[1,0,1] neg_lo:[0,0,1] neg_hi:[0,0,1]
	v_pk_fma_f32 v[116:117], v[138:139], v[124:125], v[116:117] op_sel_hi:[1,0,1] neg_lo:[0,0,1] neg_hi:[0,0,1]
	v_mul_f32_e32 v127, v119, v119
	v_mul_f32_e32 v128, v117, v117
	v_fmac_f32_e32 v127, v118, v118
	v_fmac_f32_e32 v128, v116, v116
	v_add_f32_e32 v127, v127, v128
	v_pk_mul_f32 v[128:129], v[112:113], v[126:127] op_sel_hi:[1,0]
	v_pk_mul_f32 v[112:113], v[114:115], v[126:127] op_sel_hi:[1,0]
	v_pk_fma_f32 v[114:115], v[120:121], v[124:125], v[128:129] op_sel_hi:[1,0,1] neg_lo:[0,0,1] neg_hi:[0,0,1]
	v_pk_fma_f32 v[112:113], v[122:123], v[124:125], v[112:113] op_sel_hi:[1,0,1] neg_lo:[0,0,1] neg_hi:[0,0,1]
	v_mul_f32_e32 v120, v115, v115
	v_mul_f32_e32 v121, v113, v113
	v_fmac_f32_e32 v120, v114, v114
	v_fmac_f32_e32 v121, v112, v112
	v_add_f32_e32 v120, v120, v121
	v_add_f32_e32 v122, v127, v120
	v_pk_mul_f32 v[120:121], v[104:105], v[126:127] op_sel_hi:[1,0]
	v_pk_mul_f32 v[104:105], v[106:107], v[126:127] op_sel_hi:[1,0]
	v_pk_fma_f32 v[106:107], v[108:109], v[124:125], v[120:121] op_sel_hi:[1,0,1] neg_lo:[0,0,1] neg_hi:[0,0,1]
	v_pk_fma_f32 v[104:105], v[110:111], v[124:125], v[104:105] op_sel_hi:[1,0,1] neg_lo:[0,0,1] neg_hi:[0,0,1]
	v_mul_f32_e32 v108, v107, v107
	v_mul_f32_e32 v109, v105, v105
	v_fmac_f32_e32 v108, v106, v106
	v_fmac_f32_e32 v109, v104, v104
	v_add_f32_e32 v108, v108, v109
	v_add_f32_e32 v110, v108, v122
	v_pk_mul_f32 v[108:109], v[96:97], v[126:127] op_sel_hi:[1,0]
	v_pk_mul_f32 v[96:97], v[98:99], v[126:127] op_sel_hi:[1,0]
	v_pk_fma_f32 v[98:99], v[100:101], v[124:125], v[108:109] op_sel_hi:[1,0,1] neg_lo:[0,0,1] neg_hi:[0,0,1]
	v_pk_fma_f32 v[96:97], v[102:103], v[124:125], v[96:97] op_sel_hi:[1,0,1] neg_lo:[0,0,1] neg_hi:[0,0,1]
	v_mul_f32_e32 v100, v99, v99
	v_mul_f32_e32 v101, v97, v97
	v_fmac_f32_e32 v100, v98, v98
	v_fmac_f32_e32 v101, v96, v96
	v_add_f32_e32 v100, v100, v101
	v_add_f32_e32 v102, v100, v110
	v_pk_mul_f32 v[100:101], v[88:89], v[126:127] op_sel_hi:[1,0]
	v_pk_mul_f32 v[88:89], v[90:91], v[126:127] op_sel_hi:[1,0]
	v_pk_fma_f32 v[90:91], v[92:93], v[124:125], v[100:101] op_sel_hi:[1,0,1] neg_lo:[0,0,1] neg_hi:[0,0,1]
	v_pk_fma_f32 v[88:89], v[94:95], v[124:125], v[88:89] op_sel_hi:[1,0,1] neg_lo:[0,0,1] neg_hi:[0,0,1]
	v_mul_f32_e32 v92, v91, v91
	v_mul_f32_e32 v93, v89, v89
	v_fmac_f32_e32 v92, v90, v90
	v_fmac_f32_e32 v93, v88, v88
	v_add_f32_e32 v92, v92, v93
	v_add_f32_e32 v94, v92, v102
	v_pk_mul_f32 v[92:93], v[80:81], v[126:127] op_sel_hi:[1,0]
	v_pk_mul_f32 v[80:81], v[82:83], v[126:127] op_sel_hi:[1,0]
	v_pk_fma_f32 v[82:83], v[84:85], v[124:125], v[92:93] op_sel_hi:[1,0,1] neg_lo:[0,0,1] neg_hi:[0,0,1]
	v_pk_fma_f32 v[80:81], v[86:87], v[124:125], v[80:81] op_sel_hi:[1,0,1] neg_lo:[0,0,1] neg_hi:[0,0,1]
	v_mul_f32_e32 v84, v83, v83
	v_mul_f32_e32 v85, v81, v81
	v_fmac_f32_e32 v84, v82, v82
	v_fmac_f32_e32 v85, v80, v80
	v_add_f32_e32 v84, v84, v85
	v_add_f32_e32 v86, v84, v94
	v_pk_mul_f32 v[84:85], v[72:73], v[126:127] op_sel_hi:[1,0]
	v_pk_mul_f32 v[72:73], v[74:75], v[126:127] op_sel_hi:[1,0]
	v_pk_fma_f32 v[74:75], v[76:77], v[124:125], v[84:85] op_sel_hi:[1,0,1] neg_lo:[0,0,1] neg_hi:[0,0,1]
	v_pk_fma_f32 v[72:73], v[78:79], v[124:125], v[72:73] op_sel_hi:[1,0,1] neg_lo:[0,0,1] neg_hi:[0,0,1]
	v_mul_f32_e32 v76, v75, v75
	v_mul_f32_e32 v77, v73, v73
	v_fmac_f32_e32 v76, v74, v74
	v_fmac_f32_e32 v77, v72, v72
	v_add_f32_e32 v76, v76, v77
	v_add_f32_e32 v78, v76, v86
	v_pk_mul_f32 v[76:77], v[64:65], v[126:127] op_sel_hi:[1,0]
	v_pk_mul_f32 v[64:65], v[66:67], v[126:127] op_sel_hi:[1,0]
	v_pk_fma_f32 v[66:67], v[68:69], v[124:125], v[76:77] op_sel_hi:[1,0,1] neg_lo:[0,0,1] neg_hi:[0,0,1]
	v_pk_fma_f32 v[64:65], v[70:71], v[124:125], v[64:65] op_sel_hi:[1,0,1] neg_lo:[0,0,1] neg_hi:[0,0,1]
	v_mul_f32_e32 v68, v67, v67
	v_mul_f32_e32 v69, v65, v65
	v_fmac_f32_e32 v68, v66, v66
	v_fmac_f32_e32 v69, v64, v64
	v_add_f32_e32 v68, v68, v69
	v_add_f32_e32 v70, v68, v78
	v_pk_mul_f32 v[68:69], v[56:57], v[126:127] op_sel_hi:[1,0]
	v_pk_mul_f32 v[56:57], v[58:59], v[126:127] op_sel_hi:[1,0]
	v_pk_fma_f32 v[58:59], v[60:61], v[124:125], v[68:69] op_sel_hi:[1,0,1] neg_lo:[0,0,1] neg_hi:[0,0,1]
	v_pk_fma_f32 v[56:57], v[62:63], v[124:125], v[56:57] op_sel_hi:[1,0,1] neg_lo:[0,0,1] neg_hi:[0,0,1]
	v_pk_mul_f32 v[40:41], v[40:41], v[126:127] op_sel_hi:[1,0]
	v_pk_mul_f32 v[42:43], v[42:43], v[126:127] op_sel_hi:[1,0]
	v_mul_f32_e32 v60, v59, v59
	v_mul_f32_e32 v61, v57, v57
	v_pk_fma_f32 v[50:51], v[50:51], v[124:125], v[42:43] op_sel_hi:[1,0,1] neg_lo:[0,0,1] neg_hi:[0,0,1]
	v_pk_fma_f32 v[48:49], v[48:49], v[124:125], v[40:41] op_sel_hi:[1,0,1] neg_lo:[0,0,1] neg_hi:[0,0,1]
	v_fmac_f32_e32 v60, v58, v58
	v_fmac_f32_e32 v61, v56, v56
	v_mul_f32_e32 v40, v49, v49
	v_mul_f32_e32 v41, v51, v51
	v_pk_mul_f32 v[42:43], v[52:53], v[126:127] op_sel_hi:[1,0]
	v_add_f32_e32 v60, v60, v61
	v_fmac_f32_e32 v40, v48, v48
	v_fmac_f32_e32 v41, v50, v50
	v_pk_fma_f32 v[42:43], v[44:45], v[124:125], v[42:43] op_sel_hi:[1,0,1] neg_lo:[0,0,1] neg_hi:[0,0,1]
	v_mov_b64_e32 v[44:45], s[74:75]
	v_add_f32_e32 v60, v60, v70
	v_add_f32_e32 v40, v40, v41
	v_mad_u64_u32 v[44:45], s[0:1], v144, s26, v[44:45]
	v_add_f32_e32 v60, v40, v60
	v_pk_mul_f32 v[40:41], v[54:55], v[126:127] op_sel_hi:[1,0]
	v_lshl_add_u64 v[44:45], v[44:45], 0, s[16:17]
	v_pk_fma_f32 v[40:41], v[46:47], v[124:125], v[40:41] op_sel_hi:[1,0,1] neg_lo:[0,0,1] neg_hi:[0,0,1]
	v_lshl_add_u64 v[46:47], v[44:45], 0, v[160:161]
	v_add_co_u32_e32 v44, vcc, s35, v46
	v_mul_f32_e32 v52, v43, v43
	s_nop 0
	v_addc_co_u32_e32 v45, vcc, 0, v47, vcc
	global_load_dwordx2 v[44:45], v[44:45], off
	v_mul_f32_e32 v53, v41, v41
	v_fmac_f32_e32 v52, v42, v42
	v_fmac_f32_e32 v53, v40, v40
	v_add_f32_e32 v52, v52, v53
	v_add_f32_e32 v54, v52, v60
	v_pk_mul_f32 v[52:53], v[36:37], v[126:127] op_sel_hi:[1,0]
	v_pk_mul_f32 v[36:37], v[38:39], v[126:127] op_sel_hi:[1,0]
	v_pk_fma_f32 v[38:39], v[28:29], v[124:125], v[52:53] op_sel_hi:[1,0,1] neg_lo:[0,0,1] neg_hi:[0,0,1]
	v_pk_fma_f32 v[36:37], v[30:31], v[124:125], v[36:37] op_sel_hi:[1,0,1] neg_lo:[0,0,1] neg_hi:[0,0,1]
	global_load_dwordx4 v[28:31], v[146:147], off
	v_pk_mul_f32 v[32:33], v[32:33], v[126:127] op_sel_hi:[1,0]
	v_pk_mul_f32 v[34:35], v[34:35], v[126:127] op_sel_hi:[1,0]
	v_mul_f32_e32 v52, v39, v39
	v_mul_f32_e32 v53, v37, v37
	v_pk_fma_f32 v[18:19], v[18:19], v[124:125], v[34:35] op_sel_hi:[1,0,1] neg_lo:[0,0,1] neg_hi:[0,0,1]
	v_pk_fma_f32 v[32:33], v[16:17], v[124:125], v[32:33] op_sel_hi:[1,0,1] neg_lo:[0,0,1] neg_hi:[0,0,1]
	v_fmac_f32_e32 v52, v38, v38
	v_fmac_f32_e32 v53, v36, v36
	v_mul_f32_e32 v16, v33, v33
	v_mul_f32_e32 v17, v19, v19
	v_add_f32_e32 v52, v52, v53
	v_fmac_f32_e32 v16, v32, v32
	v_fmac_f32_e32 v17, v18, v18
	v_add_f32_e32 v52, v52, v54
	v_add_f32_e32 v16, v16, v17
	v_add_f32_e32 v34, v16, v52
	v_pk_mul_f32 v[16:17], v[24:25], v[126:127] op_sel_hi:[1,0]
	v_pk_mul_f32 v[24:25], v[26:27], v[126:127] op_sel_hi:[1,0]
	v_pk_fma_f32 v[16:17], v[8:9], v[124:125], v[16:17] op_sel_hi:[1,0,1] neg_lo:[0,0,1] neg_hi:[0,0,1]
	v_pk_fma_f32 v[10:11], v[10:11], v[124:125], v[24:25] op_sel_hi:[1,0,1] neg_lo:[0,0,1] neg_hi:[0,0,1]
	v_mul_f32_e32 v8, v17, v17
	v_mul_f32_e32 v9, v11, v11
	v_fmac_f32_e32 v8, v16, v16
	v_fmac_f32_e32 v9, v10, v10
	v_add_f32_e32 v8, v8, v9
	v_add_f32_e32 v24, v8, v34
	v_pk_mul_f32 v[8:9], v[20:21], v[126:127] op_sel_hi:[1,0]
	v_pk_mul_f32 v[20:21], v[22:23], v[126:127] op_sel_hi:[1,0]
	v_pk_fma_f32 v[8:9], v[4:5], v[124:125], v[8:9] op_sel_hi:[1,0,1] neg_lo:[0,0,1] neg_hi:[0,0,1]
	v_pk_fma_f32 v[6:7], v[6:7], v[124:125], v[20:21] op_sel_hi:[1,0,1] neg_lo:[0,0,1] neg_hi:[0,0,1]
	v_mul_f32_e32 v4, v9, v9
	v_mul_f32_e32 v5, v7, v7
	v_fmac_f32_e32 v4, v8, v8
	v_fmac_f32_e32 v5, v6, v6
	v_add_f32_e32 v4, v4, v5
	v_add_f32_e32 v20, v4, v24
	v_pk_mul_f32 v[4:5], v[12:13], v[126:127] op_sel_hi:[1,0]
	v_pk_mul_f32 v[12:13], v[14:15], v[126:127] op_sel_hi:[1,0]
	v_pk_fma_f32 v[0:1], v[0:1], v[124:125], v[4:5] op_sel_hi:[1,0,1] neg_lo:[0,0,1] neg_hi:[0,0,1]
	v_pk_fma_f32 v[2:3], v[2:3], v[124:125], v[12:13] op_sel_hi:[1,0,1] neg_lo:[0,0,1] neg_hi:[0,0,1]
	v_mul_f32_e32 v4, v1, v1
	v_mul_f32_e32 v5, v3, v3
	v_fmac_f32_e32 v4, v0, v0
	v_fmac_f32_e32 v5, v2, v2
	v_add_f32_e32 v4, v4, v5
	v_add_f32_e32 v4, v4, v20
	v_mov_b32_e32 v5, v4
	s_nop 1
	v_permlane16_swap_b32_e32 v4, v5
	v_add_f32_e32 v4, v4, v5
	v_mov_b32_e32 v5, v4
	s_nop 1
	v_permlane32_swap_b32_e32 v4, v5
	v_add_f32_e32 v4, v4, v5
	v_fmamk_f32 v4, v4, 0x3b800000, v191
	v_mul_f32_e32 v5, 0x4b800000, v4
	v_cmp_gt_f32_e32 vcc, s34, v4
	v_lshlrev_b64 v[12:13], 12, v[144:145]
	v_lshl_add_u64 v[14:15], s[98:99], 0, v[12:13]
	v_cndmask_b32_e32 v4, v4, v5, vcc
	v_rsq_f32_e32 v4, v4
	v_lshl_add_u64 v[12:13], v[46:47], 0, s[20:21]
	global_load_dwordx2 v[20:21], v[12:13], off offset:480
	v_lshl_add_u64 v[14:15], v[14:15], 0, s[16:17]
	v_mul_f32_e32 v5, 0x45800000, v4
	v_cndmask_b32_e32 v4, v4, v5, vcc
	v_mul_f32_e32 v4, 0x3f4ccccd, v4
	v_lshl_add_u64 v[14:15], v[14:15], 0, v[160:161]
	s_mov_b64 s[0:1], 0
	global_load_dwordx4 v[120:123], v[146:147], off offset:64
	global_load_dwordx2 v[22:23], v[12:13], off offset:32
	global_load_dwordx4 v[124:127], v[146:147], off offset:128
	global_load_dwordx2 v[24:25], v[12:13], off offset:64
	global_load_dwordx4 v[128:131], v[146:147], off offset:192
	global_load_dwordx2 v[26:27], v[12:13], off offset:96
	global_load_dwordx4 v[132:135], v[146:147], off offset:256
	global_load_dwordx2 v[34:35], v[12:13], off offset:128
	global_load_dwordx4 v[136:139], v[146:147], off offset:320
	global_load_dwordx2 v[46:47], v[12:13], off offset:160
	global_load_dwordx4 v[140:143], v[146:147], off offset:384
	global_load_dwordx2 v[52:53], v[12:13], off offset:192
	global_load_dwordx4 v[196:199], v[146:147], off offset:448
	global_load_dwordx2 v[54:55], v[12:13], off offset:224
	global_load_dwordx4 v[200:203], v[146:147], off offset:512
	global_load_dwordx2 v[60:61], v[12:13], off offset:256
	global_load_dwordx4 v[204:207], v[146:147], off offset:576
	global_load_dwordx2 v[62:63], v[12:13], off offset:288
	global_load_dwordx4 v[208:211], v[146:147], off offset:640
	global_load_dwordx2 v[68:69], v[12:13], off offset:320
	global_load_dwordx4 v[212:215], v[146:147], off offset:704
	global_load_dwordx2 v[70:71], v[12:13], off offset:352
	global_load_dwordx4 v[216:219], v[146:147], off offset:768
	global_load_dwordx2 v[76:77], v[12:13], off offset:384
	global_load_dwordx4 v[220:223], v[146:147], off offset:832
	global_load_dwordx2 v[78:79], v[12:13], off offset:416
	global_load_dwordx4 v[224:227], v[146:147], off offset:896
	global_load_dwordx2 v[84:85], v[12:13], off offset:448
	global_load_dwordx4 v[228:231], v[146:147], off offset:960
	s_waitcnt vmcnt(30)
	v_lshlrev_b32_e32 v92, 16, v44
	v_and_b32_e32 v93, 0xffff0000, v44
	v_lshlrev_b32_e32 v94, 16, v45
	v_and_b32_e32 v95, 0xffff0000, v45
	v_mul_f32_e32 v100, 0xbfb8aa3b, v92
	v_mul_f32_e32 v101, 0xbfb8aa3b, v93
	v_mul_f32_e32 v102, 0xbfb8aa3b, v94
	v_mul_f32_e32 v103, 0xbfb8aa3b, v95
	v_exp_f32_e32 v100, v100
	v_exp_f32_e32 v101, v101
	v_exp_f32_e32 v102, v102
	v_exp_f32_e32 v103, v103
	v_pk_mul_f32 v[118:119], v[118:119], v[4:5] op_sel_hi:[1,0]
	v_pk_mul_f32 v[116:117], v[116:117], v[4:5] op_sel_hi:[1,0]
	v_add_f32_e32 v100, 1.0, v100
	v_add_f32_e32 v101, 1.0, v101
	v_add_f32_e32 v102, 1.0, v102
	v_add_f32_e32 v103, 1.0, v103
	v_rcp_f32_e32 v100, v100
	v_rcp_f32_e32 v101, v101
	v_rcp_f32_e32 v102, v102
	v_rcp_f32_e32 v103, v103
	v_pk_mul_f32 v[118:119], v[28:29], v[118:119]
	v_pk_mul_f32 v[116:117], v[30:31], v[116:117]
	v_pk_mul_f32 v[118:119], v[118:119], v[92:93]
	v_pk_mul_f32 v[116:117], v[116:117], v[94:95]
	v_pk_mul_f32 v[118:119], v[100:101], v[118:119]
	v_pk_mul_f32 v[116:117], v[102:103], v[116:117]
	v_cvt_pk_bf16_f32 v118, v118, v119
	v_cvt_pk_bf16_f32 v119, v116, v117
	global_store_dwordx2 v[14:15], v[118:119], off
	s_waitcnt vmcnt(28)
	v_lshlrev_b32_e32 v92, 16, v22
	v_and_b32_e32 v93, 0xffff0000, v22
	v_lshlrev_b32_e32 v94, 16, v23
	v_and_b32_e32 v95, 0xffff0000, v23
	v_mul_f32_e32 v100, 0xbfb8aa3b, v92
	v_mul_f32_e32 v101, 0xbfb8aa3b, v93
	v_mul_f32_e32 v102, 0xbfb8aa3b, v94
	v_mul_f32_e32 v103, 0xbfb8aa3b, v95
	v_exp_f32_e32 v100, v100
	v_exp_f32_e32 v101, v101
	v_exp_f32_e32 v102, v102
	v_exp_f32_e32 v103, v103
	v_pk_mul_f32 v[114:115], v[114:115], v[4:5] op_sel_hi:[1,0]
	v_pk_mul_f32 v[112:113], v[112:113], v[4:5] op_sel_hi:[1,0]
	v_add_f32_e32 v100, 1.0, v100
	v_add_f32_e32 v101, 1.0, v101
	v_add_f32_e32 v102, 1.0, v102
	v_add_f32_e32 v103, 1.0, v103
	v_rcp_f32_e32 v100, v100
	v_rcp_f32_e32 v101, v101
	v_rcp_f32_e32 v102, v102
	v_rcp_f32_e32 v103, v103
	v_pk_mul_f32 v[114:115], v[120:121], v[114:115]
	v_pk_mul_f32 v[112:113], v[122:123], v[112:113]
	v_pk_mul_f32 v[114:115], v[114:115], v[92:93]
	v_pk_mul_f32 v[112:113], v[112:113], v[94:95]
	v_pk_mul_f32 v[114:115], v[100:101], v[114:115]
	v_pk_mul_f32 v[112:113], v[102:103], v[112:113]
	v_cvt_pk_bf16_f32 v114, v114, v115
	v_cvt_pk_bf16_f32 v115, v112, v113
	global_store_dwordx2 v[14:15], v[114:115], off offset:32
	s_waitcnt vmcnt(27)
	v_lshlrev_b32_e32 v92, 16, v24
	v_and_b32_e32 v93, 0xffff0000, v24
	v_lshlrev_b32_e32 v94, 16, v25
	v_and_b32_e32 v95, 0xffff0000, v25
	v_mul_f32_e32 v100, 0xbfb8aa3b, v92
	v_mul_f32_e32 v101, 0xbfb8aa3b, v93
	v_mul_f32_e32 v102, 0xbfb8aa3b, v94
	v_mul_f32_e32 v103, 0xbfb8aa3b, v95
	v_exp_f32_e32 v100, v100
	v_exp_f32_e32 v101, v101
	v_exp_f32_e32 v102, v102
	v_exp_f32_e32 v103, v103
	v_pk_mul_f32 v[106:107], v[106:107], v[4:5] op_sel_hi:[1,0]
	v_pk_mul_f32 v[104:105], v[104:105], v[4:5] op_sel_hi:[1,0]
	v_add_f32_e32 v100, 1.0, v100
	v_add_f32_e32 v101, 1.0, v101
	v_add_f32_e32 v102, 1.0, v102
	v_add_f32_e32 v103, 1.0, v103
	v_rcp_f32_e32 v100, v100
	v_rcp_f32_e32 v101, v101
	v_rcp_f32_e32 v102, v102
	v_rcp_f32_e32 v103, v103
	v_pk_mul_f32 v[106:107], v[124:125], v[106:107]
	v_pk_mul_f32 v[104:105], v[126:127], v[104:105]
	v_pk_mul_f32 v[106:107], v[106:107], v[92:93]
	v_pk_mul_f32 v[104:105], v[104:105], v[94:95]
	v_pk_mul_f32 v[106:107], v[100:101], v[106:107]
	v_pk_mul_f32 v[104:105], v[102:103], v[104:105]
	v_cvt_pk_bf16_f32 v106, v106, v107
	v_cvt_pk_bf16_f32 v107, v104, v105
	global_store_dwordx2 v[14:15], v[106:107], off offset:64
	s_waitcnt vmcnt(26)
	v_lshlrev_b32_e32 v92, 16, v26
	v_and_b32_e32 v93, 0xffff0000, v26
	v_lshlrev_b32_e32 v94, 16, v27
	v_and_b32_e32 v95, 0xffff0000, v27
	v_mul_f32_e32 v100, 0xbfb8aa3b, v92
	v_mul_f32_e32 v101, 0xbfb8aa3b, v93
	v_mul_f32_e32 v102, 0xbfb8aa3b, v94
	v_mul_f32_e32 v103, 0xbfb8aa3b, v95
	v_exp_f32_e32 v100, v100
	v_exp_f32_e32 v101, v101
	v_exp_f32_e32 v102, v102
	v_exp_f32_e32 v103, v103
	v_pk_mul_f32 v[98:99], v[98:99], v[4:5] op_sel_hi:[1,0]
	v_pk_mul_f32 v[96:97], v[96:97], v[4:5] op_sel_hi:[1,0]
	v_add_f32_e32 v100, 1.0, v100
	v_add_f32_e32 v101, 1.0, v101
	v_add_f32_e32 v102, 1.0, v102
	v_add_f32_e32 v103, 1.0, v103
	v_rcp_f32_e32 v100, v100
	v_rcp_f32_e32 v101, v101
	v_rcp_f32_e32 v102, v102
	v_rcp_f32_e32 v103, v103
	v_pk_mul_f32 v[98:99], v[128:129], v[98:99]
	v_pk_mul_f32 v[96:97], v[130:131], v[96:97]
	v_pk_mul_f32 v[98:99], v[98:99], v[92:93]
	v_pk_mul_f32 v[96:97], v[96:97], v[94:95]
	v_pk_mul_f32 v[98:99], v[100:101], v[98:99]
	v_pk_mul_f32 v[96:97], v[102:103], v[96:97]
	v_cvt_pk_bf16_f32 v98, v98, v99
	v_cvt_pk_bf16_f32 v99, v96, v97
	global_store_dwordx2 v[14:15], v[98:99], off offset:96
	s_waitcnt vmcnt(25)
	v_lshlrev_b32_e32 v92, 16, v34
	v_and_b32_e32 v93, 0xffff0000, v34
	v_lshlrev_b32_e32 v94, 16, v35
	v_and_b32_e32 v95, 0xffff0000, v35
	v_mul_f32_e32 v100, 0xbfb8aa3b, v92
	v_mul_f32_e32 v101, 0xbfb8aa3b, v93
	v_mul_f32_e32 v102, 0xbfb8aa3b, v94
	v_mul_f32_e32 v103, 0xbfb8aa3b, v95
	v_exp_f32_e32 v100, v100
	v_exp_f32_e32 v101, v101
	v_exp_f32_e32 v102, v102
	v_exp_f32_e32 v103, v103
	v_pk_mul_f32 v[90:91], v[90:91], v[4:5] op_sel_hi:[1,0]
	v_pk_mul_f32 v[88:89], v[88:89], v[4:5] op_sel_hi:[1,0]
	v_add_f32_e32 v100, 1.0, v100
	v_add_f32_e32 v101, 1.0, v101
	v_add_f32_e32 v102, 1.0, v102
	v_add_f32_e32 v103, 1.0, v103
	v_rcp_f32_e32 v100, v100
	v_rcp_f32_e32 v101, v101
	v_rcp_f32_e32 v102, v102
	v_rcp_f32_e32 v103, v103
	v_pk_mul_f32 v[90:91], v[132:133], v[90:91]
	v_pk_mul_f32 v[88:89], v[134:135], v[88:89]
	v_pk_mul_f32 v[90:91], v[90:91], v[92:93]
	v_pk_mul_f32 v[88:89], v[88:89], v[94:95]
	v_pk_mul_f32 v[90:91], v[100:101], v[90:91]
	v_pk_mul_f32 v[88:89], v[102:103], v[88:89]
	v_cvt_pk_bf16_f32 v90, v90, v91
	v_cvt_pk_bf16_f32 v91, v88, v89
	global_store_dwordx2 v[14:15], v[90:91], off offset:128
	s_waitcnt vmcnt(24)
	v_lshlrev_b32_e32 v92, 16, v46
	v_and_b32_e32 v93, 0xffff0000, v46
	v_lshlrev_b32_e32 v94, 16, v47
	v_and_b32_e32 v95, 0xffff0000, v47
	v_mul_f32_e32 v100, 0xbfb8aa3b, v92
	v_mul_f32_e32 v101, 0xbfb8aa3b, v93
	v_mul_f32_e32 v102, 0xbfb8aa3b, v94
	v_mul_f32_e32 v103, 0xbfb8aa3b, v95
	v_exp_f32_e32 v100, v100
	v_exp_f32_e32 v101, v101
	v_exp_f32_e32 v102, v102
	v_exp_f32_e32 v103, v103
	v_pk_mul_f32 v[82:83], v[82:83], v[4:5] op_sel_hi:[1,0]
	v_pk_mul_f32 v[80:81], v[80:81], v[4:5] op_sel_hi:[1,0]
	v_add_f32_e32 v100, 1.0, v100
	v_add_f32_e32 v101, 1.0, v101
	v_add_f32_e32 v102, 1.0, v102
	v_add_f32_e32 v103, 1.0, v103
	v_rcp_f32_e32 v100, v100
	v_rcp_f32_e32 v101, v101
	v_rcp_f32_e32 v102, v102
	v_rcp_f32_e32 v103, v103
	v_pk_mul_f32 v[82:83], v[136:137], v[82:83]
	v_pk_mul_f32 v[80:81], v[138:139], v[80:81]
	v_pk_mul_f32 v[82:83], v[82:83], v[92:93]
	v_pk_mul_f32 v[80:81], v[80:81], v[94:95]
	v_pk_mul_f32 v[82:83], v[100:101], v[82:83]
	v_pk_mul_f32 v[80:81], v[102:103], v[80:81]
	v_cvt_pk_bf16_f32 v82, v82, v83
	v_cvt_pk_bf16_f32 v83, v80, v81
	global_store_dwordx2 v[14:15], v[82:83], off offset:160
	s_waitcnt vmcnt(23)
	v_lshlrev_b32_e32 v92, 16, v52
	v_and_b32_e32 v93, 0xffff0000, v52
	v_lshlrev_b32_e32 v94, 16, v53
	v_and_b32_e32 v95, 0xffff0000, v53
	v_mul_f32_e32 v100, 0xbfb8aa3b, v92
	v_mul_f32_e32 v101, 0xbfb8aa3b, v93
	v_mul_f32_e32 v102, 0xbfb8aa3b, v94
	v_mul_f32_e32 v103, 0xbfb8aa3b, v95
	v_exp_f32_e32 v100, v100
	v_exp_f32_e32 v101, v101
	v_exp_f32_e32 v102, v102
	v_exp_f32_e32 v103, v103
	v_pk_mul_f32 v[74:75], v[74:75], v[4:5] op_sel_hi:[1,0]
	v_pk_mul_f32 v[72:73], v[72:73], v[4:5] op_sel_hi:[1,0]
	v_add_f32_e32 v100, 1.0, v100
	v_add_f32_e32 v101, 1.0, v101
	v_add_f32_e32 v102, 1.0, v102
	v_add_f32_e32 v103, 1.0, v103
	v_rcp_f32_e32 v100, v100
	v_rcp_f32_e32 v101, v101
	v_rcp_f32_e32 v102, v102
	v_rcp_f32_e32 v103, v103
	v_pk_mul_f32 v[74:75], v[140:141], v[74:75]
	v_pk_mul_f32 v[72:73], v[142:143], v[72:73]
	v_pk_mul_f32 v[74:75], v[74:75], v[92:93]
	v_pk_mul_f32 v[72:73], v[72:73], v[94:95]
	v_pk_mul_f32 v[74:75], v[100:101], v[74:75]
	v_pk_mul_f32 v[72:73], v[102:103], v[72:73]
	v_cvt_pk_bf16_f32 v74, v74, v75
	v_cvt_pk_bf16_f32 v75, v72, v73
	global_store_dwordx2 v[14:15], v[74:75], off offset:192
	s_waitcnt vmcnt(22)
	v_lshlrev_b32_e32 v92, 16, v54
	v_and_b32_e32 v93, 0xffff0000, v54
	v_lshlrev_b32_e32 v94, 16, v55
	v_and_b32_e32 v95, 0xffff0000, v55
	v_mul_f32_e32 v100, 0xbfb8aa3b, v92
	v_mul_f32_e32 v101, 0xbfb8aa3b, v93
	v_mul_f32_e32 v102, 0xbfb8aa3b, v94
	v_mul_f32_e32 v103, 0xbfb8aa3b, v95
	v_exp_f32_e32 v100, v100
	v_exp_f32_e32 v101, v101
	v_exp_f32_e32 v102, v102
	v_exp_f32_e32 v103, v103
	v_pk_mul_f32 v[66:67], v[66:67], v[4:5] op_sel_hi:[1,0]
	v_pk_mul_f32 v[64:65], v[64:65], v[4:5] op_sel_hi:[1,0]
	v_add_f32_e32 v100, 1.0, v100
	v_add_f32_e32 v101, 1.0, v101
	v_add_f32_e32 v102, 1.0, v102
	v_add_f32_e32 v103, 1.0, v103
	v_rcp_f32_e32 v100, v100
	v_rcp_f32_e32 v101, v101
	v_rcp_f32_e32 v102, v102
	v_rcp_f32_e32 v103, v103
	v_pk_mul_f32 v[66:67], v[196:197], v[66:67]
	v_pk_mul_f32 v[64:65], v[198:199], v[64:65]
	v_pk_mul_f32 v[66:67], v[66:67], v[92:93]
	v_pk_mul_f32 v[64:65], v[64:65], v[94:95]
	v_pk_mul_f32 v[66:67], v[100:101], v[66:67]
	v_pk_mul_f32 v[64:65], v[102:103], v[64:65]
	v_cvt_pk_bf16_f32 v66, v66, v67
	v_cvt_pk_bf16_f32 v67, v64, v65
	global_store_dwordx2 v[14:15], v[66:67], off offset:224
	s_waitcnt vmcnt(21)
	v_lshlrev_b32_e32 v92, 16, v60
	v_and_b32_e32 v93, 0xffff0000, v60
	v_lshlrev_b32_e32 v94, 16, v61
	v_and_b32_e32 v95, 0xffff0000, v61
	v_mul_f32_e32 v100, 0xbfb8aa3b, v92
	v_mul_f32_e32 v101, 0xbfb8aa3b, v93
	v_mul_f32_e32 v102, 0xbfb8aa3b, v94
	v_mul_f32_e32 v103, 0xbfb8aa3b, v95
	v_exp_f32_e32 v100, v100
	v_exp_f32_e32 v101, v101
	v_exp_f32_e32 v102, v102
	v_exp_f32_e32 v103, v103
	v_pk_mul_f32 v[58:59], v[58:59], v[4:5] op_sel_hi:[1,0]
	v_pk_mul_f32 v[56:57], v[56:57], v[4:5] op_sel_hi:[1,0]
	v_add_f32_e32 v100, 1.0, v100
	v_add_f32_e32 v101, 1.0, v101
	v_add_f32_e32 v102, 1.0, v102
	v_add_f32_e32 v103, 1.0, v103
	v_rcp_f32_e32 v100, v100
	v_rcp_f32_e32 v101, v101
	v_rcp_f32_e32 v102, v102
	v_rcp_f32_e32 v103, v103
	v_pk_mul_f32 v[58:59], v[200:201], v[58:59]
	v_pk_mul_f32 v[56:57], v[202:203], v[56:57]
	v_pk_mul_f32 v[58:59], v[58:59], v[92:93]
	v_pk_mul_f32 v[56:57], v[56:57], v[94:95]
	v_pk_mul_f32 v[58:59], v[100:101], v[58:59]
	v_pk_mul_f32 v[56:57], v[102:103], v[56:57]
	v_cvt_pk_bf16_f32 v58, v58, v59
	v_cvt_pk_bf16_f32 v59, v56, v57
	global_store_dwordx2 v[14:15], v[58:59], off offset:256
	s_waitcnt vmcnt(20)
	v_lshlrev_b32_e32 v92, 16, v62
	v_and_b32_e32 v93, 0xffff0000, v62
	v_lshlrev_b32_e32 v94, 16, v63
	v_and_b32_e32 v95, 0xffff0000, v63
	v_mul_f32_e32 v100, 0xbfb8aa3b, v92
	v_mul_f32_e32 v101, 0xbfb8aa3b, v93
	v_mul_f32_e32 v102, 0xbfb8aa3b, v94
	v_mul_f32_e32 v103, 0xbfb8aa3b, v95
	v_exp_f32_e32 v100, v100
	v_exp_f32_e32 v101, v101
	v_exp_f32_e32 v102, v102
	v_exp_f32_e32 v103, v103
	v_pk_mul_f32 v[48:49], v[48:49], v[4:5] op_sel_hi:[1,0]
	v_pk_mul_f32 v[50:51], v[50:51], v[4:5] op_sel_hi:[1,0]
	v_add_f32_e32 v100, 1.0, v100
	v_add_f32_e32 v101, 1.0, v101
	v_add_f32_e32 v102, 1.0, v102
	v_add_f32_e32 v103, 1.0, v103
	v_rcp_f32_e32 v100, v100
	v_rcp_f32_e32 v101, v101
	v_rcp_f32_e32 v102, v102
	v_rcp_f32_e32 v103, v103
	v_pk_mul_f32 v[48:49], v[204:205], v[48:49]
	v_pk_mul_f32 v[50:51], v[206:207], v[50:51]
	v_pk_mul_f32 v[48:49], v[48:49], v[92:93]
	v_pk_mul_f32 v[50:51], v[50:51], v[94:95]
	v_pk_mul_f32 v[48:49], v[100:101], v[48:49]
	v_pk_mul_f32 v[50:51], v[102:103], v[50:51]
	v_cvt_pk_bf16_f32 v48, v48, v49
	v_cvt_pk_bf16_f32 v49, v50, v51
	global_store_dwordx2 v[14:15], v[48:49], off offset:288
	s_waitcnt vmcnt(19)
	v_lshlrev_b32_e32 v92, 16, v68
	v_and_b32_e32 v93, 0xffff0000, v68
	v_lshlrev_b32_e32 v94, 16, v69
	v_and_b32_e32 v95, 0xffff0000, v69
	v_mul_f32_e32 v100, 0xbfb8aa3b, v92
	v_mul_f32_e32 v101, 0xbfb8aa3b, v93
	v_mul_f32_e32 v102, 0xbfb8aa3b, v94
	v_mul_f32_e32 v103, 0xbfb8aa3b, v95
	v_exp_f32_e32 v100, v100
	v_exp_f32_e32 v101, v101
	v_exp_f32_e32 v102, v102
	v_exp_f32_e32 v103, v103
	v_pk_mul_f32 v[42:43], v[42:43], v[4:5] op_sel_hi:[1,0]
	v_pk_mul_f32 v[40:41], v[40:41], v[4:5] op_sel_hi:[1,0]
	v_add_f32_e32 v100, 1.0, v100
	v_add_f32_e32 v101, 1.0, v101
	v_add_f32_e32 v102, 1.0, v102
	v_add_f32_e32 v103, 1.0, v103
	v_rcp_f32_e32 v100, v100
	v_rcp_f32_e32 v101, v101
	v_rcp_f32_e32 v102, v102
	v_rcp_f32_e32 v103, v103
	v_pk_mul_f32 v[42:43], v[208:209], v[42:43]
	v_pk_mul_f32 v[40:41], v[210:211], v[40:41]
	v_pk_mul_f32 v[42:43], v[42:43], v[92:93]
	v_pk_mul_f32 v[40:41], v[40:41], v[94:95]
	v_pk_mul_f32 v[42:43], v[100:101], v[42:43]
	v_pk_mul_f32 v[40:41], v[102:103], v[40:41]
	v_cvt_pk_bf16_f32 v42, v42, v43
	v_cvt_pk_bf16_f32 v43, v40, v41
	global_store_dwordx2 v[14:15], v[42:43], off offset:320
	s_waitcnt vmcnt(18)
	v_lshlrev_b32_e32 v92, 16, v70
	v_and_b32_e32 v93, 0xffff0000, v70
	v_lshlrev_b32_e32 v94, 16, v71
	v_and_b32_e32 v95, 0xffff0000, v71
	v_mul_f32_e32 v100, 0xbfb8aa3b, v92
	v_mul_f32_e32 v101, 0xbfb8aa3b, v93
	v_mul_f32_e32 v102, 0xbfb8aa3b, v94
	v_mul_f32_e32 v103, 0xbfb8aa3b, v95
	v_exp_f32_e32 v100, v100
	v_exp_f32_e32 v101, v101
	v_exp_f32_e32 v102, v102
	v_exp_f32_e32 v103, v103
	v_pk_mul_f32 v[38:39], v[38:39], v[4:5] op_sel_hi:[1,0]
	v_pk_mul_f32 v[36:37], v[36:37], v[4:5] op_sel_hi:[1,0]
	v_add_f32_e32 v100, 1.0, v100
	v_add_f32_e32 v101, 1.0, v101
	v_add_f32_e32 v102, 1.0, v102
	v_add_f32_e32 v103, 1.0, v103
	v_rcp_f32_e32 v100, v100
	v_rcp_f32_e32 v101, v101
	v_rcp_f32_e32 v102, v102
	v_rcp_f32_e32 v103, v103
	v_pk_mul_f32 v[38:39], v[212:213], v[38:39]
	v_pk_mul_f32 v[36:37], v[214:215], v[36:37]
	v_pk_mul_f32 v[38:39], v[38:39], v[92:93]
	v_pk_mul_f32 v[36:37], v[36:37], v[94:95]
	v_pk_mul_f32 v[38:39], v[100:101], v[38:39]
	v_pk_mul_f32 v[36:37], v[102:103], v[36:37]
	v_cvt_pk_bf16_f32 v38, v38, v39
	v_cvt_pk_bf16_f32 v39, v36, v37
	global_store_dwordx2 v[14:15], v[38:39], off offset:352
	s_waitcnt vmcnt(17)
	v_lshlrev_b32_e32 v92, 16, v76
	v_and_b32_e32 v93, 0xffff0000, v76
	v_lshlrev_b32_e32 v94, 16, v77
	v_and_b32_e32 v95, 0xffff0000, v77
	v_mul_f32_e32 v100, 0xbfb8aa3b, v92
	v_mul_f32_e32 v101, 0xbfb8aa3b, v93
	v_mul_f32_e32 v102, 0xbfb8aa3b, v94
	v_mul_f32_e32 v103, 0xbfb8aa3b, v95
	v_exp_f32_e32 v100, v100
	v_exp_f32_e32 v101, v101
	v_exp_f32_e32 v102, v102
	v_exp_f32_e32 v103, v103
	v_pk_mul_f32 v[32:33], v[32:33], v[4:5] op_sel_hi:[1,0]
	v_pk_mul_f32 v[18:19], v[18:19], v[4:5] op_sel_hi:[1,0]
	v_add_f32_e32 v100, 1.0, v100
	v_add_f32_e32 v101, 1.0, v101
	v_add_f32_e32 v102, 1.0, v102
	v_add_f32_e32 v103, 1.0, v103
	v_rcp_f32_e32 v100, v100
	v_rcp_f32_e32 v101, v101
	v_rcp_f32_e32 v102, v102
	v_rcp_f32_e32 v103, v103
	v_pk_mul_f32 v[32:33], v[216:217], v[32:33]
	v_pk_mul_f32 v[18:19], v[218:219], v[18:19]
	v_pk_mul_f32 v[32:33], v[32:33], v[92:93]
	v_pk_mul_f32 v[18:19], v[18:19], v[94:95]
	v_pk_mul_f32 v[32:33], v[100:101], v[32:33]
	v_pk_mul_f32 v[18:19], v[102:103], v[18:19]
	v_cvt_pk_bf16_f32 v32, v32, v33
	v_cvt_pk_bf16_f32 v33, v18, v19
	global_store_dwordx2 v[14:15], v[32:33], off offset:384
	s_waitcnt vmcnt(16)
	v_lshlrev_b32_e32 v92, 16, v78
	v_and_b32_e32 v93, 0xffff0000, v78
	v_lshlrev_b32_e32 v94, 16, v79
	v_and_b32_e32 v95, 0xffff0000, v79
	v_mul_f32_e32 v100, 0xbfb8aa3b, v92
	v_mul_f32_e32 v101, 0xbfb8aa3b, v93
	v_mul_f32_e32 v102, 0xbfb8aa3b, v94
	v_mul_f32_e32 v103, 0xbfb8aa3b, v95
	v_exp_f32_e32 v100, v100
	v_exp_f32_e32 v101, v101
	v_exp_f32_e32 v102, v102
	v_exp_f32_e32 v103, v103
	v_pk_mul_f32 v[16:17], v[16:17], v[4:5] op_sel_hi:[1,0]
	v_pk_mul_f32 v[10:11], v[10:11], v[4:5] op_sel_hi:[1,0]
	v_add_f32_e32 v100, 1.0, v100
	v_add_f32_e32 v101, 1.0, v101
	v_add_f32_e32 v102, 1.0, v102
	v_add_f32_e32 v103, 1.0, v103
	v_rcp_f32_e32 v100, v100
	v_rcp_f32_e32 v101, v101
	v_rcp_f32_e32 v102, v102
	v_rcp_f32_e32 v103, v103
	v_pk_mul_f32 v[16:17], v[220:221], v[16:17]
	v_pk_mul_f32 v[10:11], v[222:223], v[10:11]
	v_pk_mul_f32 v[16:17], v[16:17], v[92:93]
	v_pk_mul_f32 v[10:11], v[10:11], v[94:95]
	v_pk_mul_f32 v[16:17], v[100:101], v[16:17]
	v_pk_mul_f32 v[10:11], v[102:103], v[10:11]
	v_cvt_pk_bf16_f32 v16, v16, v17
	v_cvt_pk_bf16_f32 v17, v10, v11
	global_store_dwordx2 v[14:15], v[16:17], off offset:416
	s_waitcnt vmcnt(15)
	v_lshlrev_b32_e32 v92, 16, v84
	v_and_b32_e32 v93, 0xffff0000, v84
	v_lshlrev_b32_e32 v94, 16, v85
	v_and_b32_e32 v95, 0xffff0000, v85
	v_mul_f32_e32 v100, 0xbfb8aa3b, v92
	v_mul_f32_e32 v101, 0xbfb8aa3b, v93
	v_mul_f32_e32 v102, 0xbfb8aa3b, v94
	v_mul_f32_e32 v103, 0xbfb8aa3b, v95
	v_exp_f32_e32 v100, v100
	v_exp_f32_e32 v101, v101
	v_exp_f32_e32 v102, v102
	v_exp_f32_e32 v103, v103
	v_pk_mul_f32 v[8:9], v[8:9], v[4:5] op_sel_hi:[1,0]
	v_pk_mul_f32 v[6:7], v[6:7], v[4:5] op_sel_hi:[1,0]
	v_add_f32_e32 v100, 1.0, v100
	v_add_f32_e32 v101, 1.0, v101
	v_add_f32_e32 v102, 1.0, v102
	v_add_f32_e32 v103, 1.0, v103
	v_rcp_f32_e32 v100, v100
	v_rcp_f32_e32 v101, v101
	v_rcp_f32_e32 v102, v102
	v_rcp_f32_e32 v103, v103
	v_pk_mul_f32 v[8:9], v[224:225], v[8:9]
	v_pk_mul_f32 v[6:7], v[226:227], v[6:7]
	v_pk_mul_f32 v[8:9], v[8:9], v[92:93]
	v_pk_mul_f32 v[6:7], v[6:7], v[94:95]
	v_pk_mul_f32 v[8:9], v[100:101], v[8:9]
	v_pk_mul_f32 v[6:7], v[102:103], v[6:7]
	v_cvt_pk_bf16_f32 v8, v8, v9
	v_cvt_pk_bf16_f32 v9, v6, v7
	global_store_dwordx2 v[14:15], v[8:9], off offset:448
	s_waitcnt vmcnt(15)
	v_lshlrev_b32_e32 v92, 16, v20
	v_and_b32_e32 v93, 0xffff0000, v20
	v_lshlrev_b32_e32 v94, 16, v21
	v_and_b32_e32 v95, 0xffff0000, v21
	v_mul_f32_e32 v100, 0xbfb8aa3b, v92
	v_mul_f32_e32 v101, 0xbfb8aa3b, v93
	v_mul_f32_e32 v102, 0xbfb8aa3b, v94
	v_mul_f32_e32 v103, 0xbfb8aa3b, v95
	v_exp_f32_e32 v100, v100
	v_exp_f32_e32 v101, v101
	v_exp_f32_e32 v102, v102
	v_exp_f32_e32 v103, v103
	v_pk_mul_f32 v[0:1], v[0:1], v[4:5] op_sel_hi:[1,0]
	v_pk_mul_f32 v[2:3], v[2:3], v[4:5] op_sel_hi:[1,0]
	v_add_f32_e32 v100, 1.0, v100
	v_add_f32_e32 v101, 1.0, v101
	v_add_f32_e32 v102, 1.0, v102
	v_add_f32_e32 v103, 1.0, v103
	v_rcp_f32_e32 v100, v100
	v_rcp_f32_e32 v101, v101
	v_rcp_f32_e32 v102, v102
	v_rcp_f32_e32 v103, v103
	v_pk_mul_f32 v[0:1], v[228:229], v[0:1]
	v_pk_mul_f32 v[2:3], v[230:231], v[2:3]
	v_pk_mul_f32 v[0:1], v[0:1], v[92:93]
	v_pk_mul_f32 v[2:3], v[2:3], v[94:95]
	v_pk_mul_f32 v[0:1], v[100:101], v[0:1]
	v_pk_mul_f32 v[2:3], v[102:103], v[2:3]
	v_cvt_pk_bf16_f32 v0, v0, v1
	v_cvt_pk_bf16_f32 v1, v2, v3
	global_store_dwordx2 v[14:15], v[0:1], off offset:480
